# GEMM K-loops: LDS-DMA issue 3,5,3,5 pieces per phase (one q0 and one q2 piece moved), waits vmcnt(8,7,8,7)
# baseline (speedup 1.0000x reference)
.LBB0_140:
	s_add_u32 s10, s8, 0xfff80080
	s_addc_u32 s11, s9, -1
	s_add_i32 s60, 0, 0x10000
	s_cmp_eq_u32 s59, 28
	s_cselect_b32 s15, s0, s11
	s_cselect_b32 s14, s1, s10
	v_add_u32_e32 v0, s60, v167
	s_cselect_b32 s11, s25, s58
	s_cselect_b32 s10, s27, s57
	s_add_i32 s62, 0, 0x14000
	ds_read_b128 v[130:133], v0
	ds_read_b128 v[158:161], v0 offset:1024
	ds_read_b128 v[162:165], v0 offset:2048
	ds_read_b128 v[170:173], v0 offset:3072
	v_add_u32_e32 v0, s62, v167
	ds_read_b128 v[174:177], v0
	ds_read_b128 v[178:181], v0 offset:1024
	ds_read_b128 v[182:185], v0 offset:2048
	ds_read_b128 v[186:189], v0 offset:3072
	s_mov_b32 m0, s53
	s_nop 0
	global_load_lds_dwordx4 v136, s[74:75]
	s_add_i32 m0, s48, 0xc000
	ds_read_b128 v[190:193], v169
	ds_read_b128 v[194:197], v169 offset:1024
	ds_read_b128 v[198:201], v169 offset:2048
	ds_read_b128 v[216:219], v169 offset:3072
	ds_read_b128 v[220:223], v169 offset:4096
	ds_read_b128 v[224:227], v169 offset:5120
	ds_read_b128 v[228:231], v169 offset:6144
	ds_read_b128 v[232:235], v169 offset:7168
	global_load_lds_dwordx4 v156, s[8:9]
	s_add_i32 m0, s48, 0xe000
	s_nop 0
	global_load_lds_dwordx4 v146, s[8:9]
	s_waitcnt vmcnt(8)
	s_waitcnt lgkmcnt(0)
	s_barrier
	s_setprio 1
	s_waitcnt lgkmcnt(0)
	v_mfma_f32_16x16x32_bf16 v[126:129], v[130:133], v[190:193], v[126:129]
	v_mfma_f32_16x16x32_bf16 v[122:125], v[162:165], v[190:193], v[122:125]
	v_mfma_f32_16x16x32_bf16 v[110:113], v[130:133], v[198:201], v[110:113]
	v_mfma_f32_16x16x32_bf16 v[106:109], v[162:165], v[198:201], v[106:109]
	v_mfma_f32_16x16x32_bf16 v[94:97], v[130:133], v[220:223], v[94:97]
	v_mfma_f32_16x16x32_bf16 v[90:93], v[162:165], v[220:223], v[90:93]
	v_mfma_f32_16x16x32_bf16 v[78:81], v[130:133], v[228:231], v[78:81]
	v_mfma_f32_16x16x32_bf16 v[74:77], v[162:165], v[228:231], v[74:77]
	v_mfma_f32_16x16x32_bf16 v[126:129], v[158:161], v[194:197], v[126:129]
	v_mfma_f32_16x16x32_bf16 v[122:125], v[170:173], v[194:197], v[122:125]
	v_mfma_f32_16x16x32_bf16 v[110:113], v[158:161], v[216:219], v[110:113]
	v_mfma_f32_16x16x32_bf16 v[106:109], v[170:173], v[216:219], v[106:109]
	v_mfma_f32_16x16x32_bf16 v[94:97], v[158:161], v[224:227], v[94:97]
	v_mfma_f32_16x16x32_bf16 v[90:93], v[170:173], v[224:227], v[90:93]
	v_mfma_f32_16x16x32_bf16 v[78:81], v[158:161], v[232:235], v[78:81]
	v_mfma_f32_16x16x32_bf16 v[74:77], v[170:173], v[232:235], v[74:77]
	s_setprio 0
	s_setprio 1
	v_mfma_f32_16x16x32_bf16 v[118:121], v[174:177], v[190:193], v[118:121]
	v_mfma_f32_16x16x32_bf16 v[114:117], v[182:185], v[190:193], v[114:117]
	v_mfma_f32_16x16x32_bf16 v[102:105], v[174:177], v[198:201], v[102:105]
	v_mfma_f32_16x16x32_bf16 v[98:101], v[182:185], v[198:201], v[98:101]
	v_mfma_f32_16x16x32_bf16 v[86:89], v[174:177], v[220:223], v[86:89]
	v_mfma_f32_16x16x32_bf16 v[82:85], v[182:185], v[220:223], v[82:85]
	v_mfma_f32_16x16x32_bf16 v[70:73], v[174:177], v[228:231], v[70:73]
	v_mfma_f32_16x16x32_bf16 v[66:69], v[182:185], v[228:231], v[66:69]
	v_mfma_f32_16x16x32_bf16 v[118:121], v[178:181], v[194:197], v[118:121]
	v_mfma_f32_16x16x32_bf16 v[114:117], v[186:189], v[194:197], v[114:117]
	v_mfma_f32_16x16x32_bf16 v[102:105], v[178:181], v[216:219], v[102:105]
	v_mfma_f32_16x16x32_bf16 v[98:101], v[186:189], v[216:219], v[98:101]
	v_mfma_f32_16x16x32_bf16 v[86:89], v[178:181], v[224:227], v[86:89]
	v_mfma_f32_16x16x32_bf16 v[82:85], v[186:189], v[224:227], v[82:85]
	v_mfma_f32_16x16x32_bf16 v[70:73], v[178:181], v[232:235], v[70:73]
	v_mfma_f32_16x16x32_bf16 v[66:69], v[186:189], v[232:235], v[66:69]
	s_setprio 0
	s_barrier
	s_add_i32 s60, s60, s29
	s_add_u32 s72, s10, s44
	s_addc_u32 s73, s11, s45
	s_mov_b32 m0, s60
	ds_read_b128 v[190:193], v169 offset:16384
	ds_read_b128 v[194:197], v169 offset:17408
	ds_read_b128 v[198:201], v169 offset:18432
	ds_read_b128 v[216:219], v169 offset:19456
	ds_read_b128 v[220:223], v169 offset:20480
	ds_read_b128 v[224:227], v169 offset:21504
	ds_read_b128 v[228:231], v169 offset:22528
	ds_read_b128 v[232:235], v169 offset:23552
	global_load_lds_dwordx4 v138, s[10:11]
	s_add_i32 m0, s60, 0x2000
	s_add_u32 s60, s10, 0x80000
	s_addc_u32 s61, s11, 0
	s_add_i32 s62, s62, s29
	global_load_lds_dwordx4 v134, s[10:11]
	s_mov_b32 m0, s62
	s_add_u32 s74, s14, s44
	s_addc_u32 s75, s15, s45
	global_load_lds_dwordx4 v138, s[60:61]
	s_add_i32 m0, s62, 0x2000
	s_nop 0
	global_load_lds_dwordx4 v134, s[60:61]
	s_mov_b32 m0, s48
	s_nop 0
	global_load_lds_dwordx4 v140, s[14:15]
	s_waitcnt vmcnt(7)
	s_waitcnt lgkmcnt(0)
	s_barrier
	s_setprio 1
	s_waitcnt lgkmcnt(0)
	v_mfma_f32_16x16x32_bf16 v[62:65], v[130:133], v[190:193], v[62:65]
	v_mfma_f32_16x16x32_bf16 v[58:61], v[162:165], v[190:193], v[58:61]
	v_mfma_f32_16x16x32_bf16 v[46:49], v[130:133], v[198:201], v[46:49]
	v_mfma_f32_16x16x32_bf16 v[42:45], v[162:165], v[198:201], v[42:45]
	v_mfma_f32_16x16x32_bf16 v[30:33], v[130:133], v[220:223], v[30:33]
	v_mfma_f32_16x16x32_bf16 v[26:29], v[162:165], v[220:223], v[26:29]
	v_mfma_f32_16x16x32_bf16 v[14:17], v[130:133], v[228:231], v[14:17]
	v_mfma_f32_16x16x32_bf16 v[10:13], v[162:165], v[228:231], v[10:13]
	v_mfma_f32_16x16x32_bf16 v[62:65], v[158:161], v[194:197], v[62:65]
	v_mfma_f32_16x16x32_bf16 v[58:61], v[170:173], v[194:197], v[58:61]
	v_mfma_f32_16x16x32_bf16 v[46:49], v[158:161], v[216:219], v[46:49]
	v_mfma_f32_16x16x32_bf16 v[42:45], v[170:173], v[216:219], v[42:45]
	v_mfma_f32_16x16x32_bf16 v[30:33], v[158:161], v[224:227], v[30:33]
	v_mfma_f32_16x16x32_bf16 v[26:29], v[170:173], v[224:227], v[26:29]
	v_mfma_f32_16x16x32_bf16 v[14:17], v[158:161], v[232:235], v[14:17]
	v_mfma_f32_16x16x32_bf16 v[10:13], v[170:173], v[232:235], v[10:13]
	s_setprio 0
	s_setprio 1
	v_mfma_f32_16x16x32_bf16 v[54:57], v[174:177], v[190:193], v[54:57]
	v_mfma_f32_16x16x32_bf16 v[50:53], v[182:185], v[190:193], v[50:53]
	v_mfma_f32_16x16x32_bf16 v[38:41], v[174:177], v[198:201], v[38:41]
	v_mfma_f32_16x16x32_bf16 v[34:37], v[182:185], v[198:201], v[34:37]
	v_mfma_f32_16x16x32_bf16 v[22:25], v[174:177], v[220:223], v[22:25]
	v_mfma_f32_16x16x32_bf16 v[18:21], v[182:185], v[220:223], v[18:21]
	v_mfma_f32_16x16x32_bf16 v[6:9], v[174:177], v[228:231], v[6:9]
	v_mfma_f32_16x16x32_bf16 v[2:5], v[182:185], v[228:231], v[2:5]
	v_mfma_f32_16x16x32_bf16 v[54:57], v[178:181], v[194:197], v[54:57]
	v_mfma_f32_16x16x32_bf16 v[50:53], v[186:189], v[194:197], v[50:53]
	v_mfma_f32_16x16x32_bf16 v[38:41], v[178:181], v[216:219], v[38:41]
	v_mfma_f32_16x16x32_bf16 v[34:37], v[186:189], v[216:219], v[34:37]
	v_mfma_f32_16x16x32_bf16 v[22:25], v[178:181], v[224:227], v[22:25]
	v_mfma_f32_16x16x32_bf16 v[18:21], v[186:189], v[224:227], v[18:21]
	v_mfma_f32_16x16x32_bf16 v[6:9], v[178:181], v[232:235], v[6:9]
	v_mfma_f32_16x16x32_bf16 v[2:5], v[186:189], v[232:235], v[2:5]
	s_setprio 0
	s_barrier
	s_add_i32 s60, 0, 0x18000
	v_add_u32_e32 v0, s60, v167
	s_add_i32 s61, 0, 0x1c000
	ds_read_b128 v[130:133], v0
	ds_read_b128 v[158:161], v0 offset:1024
	ds_read_b128 v[162:165], v0 offset:2048
	ds_read_b128 v[170:173], v0 offset:3072
	v_add_u32_e32 v0, s61, v167
	ds_read_b128 v[174:177], v0
	ds_read_b128 v[178:181], v0 offset:1024
	ds_read_b128 v[182:185], v0 offset:2048
	ds_read_b128 v[186:189], v0 offset:3072
	s_mov_b32 m0, s49
	s_nop 0
	global_load_lds_dwordx4 v136, s[14:15]
	s_add_u32 s14, s14, 0x80000
	s_addc_u32 s15, s15, 0
	s_mov_b32 m0, s50
	ds_read_b128 v[190:193], v169 offset:32768
	ds_read_b128 v[194:197], v169 offset:33792
	ds_read_b128 v[198:201], v169 offset:34816
	ds_read_b128 v[216:219], v169 offset:35840
	ds_read_b128 v[220:223], v169 offset:36864
	ds_read_b128 v[224:227], v169 offset:37888
	ds_read_b128 v[228:231], v169 offset:38912
	ds_read_b128 v[232:235], v169 offset:39936
	global_load_lds_dwordx4 v140, s[14:15]
	s_mov_b32 m0, s51
	s_nop 0
	global_load_lds_dwordx4 v136, s[14:15]
	s_waitcnt vmcnt(8)
	s_waitcnt lgkmcnt(0)
	s_barrier
	s_setprio 1
	s_waitcnt lgkmcnt(0)
	v_mfma_f32_16x16x32_bf16 v[126:129], v[130:133], v[190:193], v[126:129]
	v_mfma_f32_16x16x32_bf16 v[122:125], v[162:165], v[190:193], v[122:125]
	v_mfma_f32_16x16x32_bf16 v[110:113], v[130:133], v[198:201], v[110:113]
	v_mfma_f32_16x16x32_bf16 v[106:109], v[162:165], v[198:201], v[106:109]
	v_mfma_f32_16x16x32_bf16 v[94:97], v[130:133], v[220:223], v[94:97]
	v_mfma_f32_16x16x32_bf16 v[90:93], v[162:165], v[220:223], v[90:93]
	v_mfma_f32_16x16x32_bf16 v[78:81], v[130:133], v[228:231], v[78:81]
	v_mfma_f32_16x16x32_bf16 v[74:77], v[162:165], v[228:231], v[74:77]
	v_mfma_f32_16x16x32_bf16 v[126:129], v[158:161], v[194:197], v[126:129]
	v_mfma_f32_16x16x32_bf16 v[122:125], v[170:173], v[194:197], v[122:125]
	v_mfma_f32_16x16x32_bf16 v[110:113], v[158:161], v[216:219], v[110:113]
	v_mfma_f32_16x16x32_bf16 v[106:109], v[170:173], v[216:219], v[106:109]
	v_mfma_f32_16x16x32_bf16 v[94:97], v[158:161], v[224:227], v[94:97]
	v_mfma_f32_16x16x32_bf16 v[90:93], v[170:173], v[224:227], v[90:93]
	v_mfma_f32_16x16x32_bf16 v[78:81], v[158:161], v[232:235], v[78:81]
	v_mfma_f32_16x16x32_bf16 v[74:77], v[170:173], v[232:235], v[74:77]
	s_setprio 0
	s_setprio 1
	v_mfma_f32_16x16x32_bf16 v[118:121], v[174:177], v[190:193], v[118:121]
	v_mfma_f32_16x16x32_bf16 v[114:117], v[182:185], v[190:193], v[114:117]
	v_mfma_f32_16x16x32_bf16 v[102:105], v[174:177], v[198:201], v[102:105]
	v_mfma_f32_16x16x32_bf16 v[98:101], v[182:185], v[198:201], v[98:101]
	v_mfma_f32_16x16x32_bf16 v[86:89], v[174:177], v[220:223], v[86:89]
	v_mfma_f32_16x16x32_bf16 v[82:85], v[182:185], v[220:223], v[82:85]
	v_mfma_f32_16x16x32_bf16 v[70:73], v[174:177], v[228:231], v[70:73]
	v_mfma_f32_16x16x32_bf16 v[66:69], v[182:185], v[228:231], v[66:69]
	v_mfma_f32_16x16x32_bf16 v[118:121], v[178:181], v[194:197], v[118:121]
	v_mfma_f32_16x16x32_bf16 v[114:117], v[186:189], v[194:197], v[114:117]
	v_mfma_f32_16x16x32_bf16 v[102:105], v[178:181], v[216:219], v[102:105]
	v_mfma_f32_16x16x32_bf16 v[98:101], v[186:189], v[216:219], v[98:101]
	v_mfma_f32_16x16x32_bf16 v[86:89], v[178:181], v[224:227], v[86:89]
	v_mfma_f32_16x16x32_bf16 v[82:85], v[186:189], v[224:227], v[82:85]
	v_mfma_f32_16x16x32_bf16 v[70:73], v[178:181], v[232:235], v[70:73]
	v_mfma_f32_16x16x32_bf16 v[66:69], v[186:189], v[232:235], v[66:69]
	s_setprio 0
	s_barrier
	s_add_i32 s14, s60, s29
	s_mov_b32 m0, s14
	ds_read_b128 v[190:193], v169 offset:49152
	ds_read_b128 v[194:197], v169 offset:50176
	ds_read_b128 v[198:201], v169 offset:51200
	ds_read_b128 v[216:219], v169 offset:52224
	ds_read_b128 v[220:223], v169 offset:53248
	ds_read_b128 v[224:227], v169 offset:54272
	ds_read_b128 v[228:231], v169 offset:55296
	ds_read_b128 v[232:235], v169 offset:56320
	global_load_lds_dwordx4 v138, s[72:73]
	s_add_i32 m0, s14, 0x2000
	s_add_u32 s10, s10, 0x80080
	s_addc_u32 s11, s11, 0
	s_add_i32 s14, s61, s29
	global_load_lds_dwordx4 v134, s[72:73]
	s_mov_b32 m0, s14
	s_nop 0
	global_load_lds_dwordx4 v138, s[10:11]
	s_add_i32 m0, s14, 0x2000
	s_nop 0
	global_load_lds_dwordx4 v134, s[10:11]
	s_mov_b32 m0, s52
	s_nop 0
	global_load_lds_dwordx4 v140, s[74:75]
	s_waitcnt vmcnt(7)
	s_waitcnt lgkmcnt(0)
	s_barrier
	s_setprio 1
	s_waitcnt lgkmcnt(0)
	v_mfma_f32_16x16x32_bf16 v[62:65], v[130:133], v[190:193], v[62:65]
	v_mfma_f32_16x16x32_bf16 v[58:61], v[162:165], v[190:193], v[58:61]
	v_mfma_f32_16x16x32_bf16 v[46:49], v[130:133], v[198:201], v[46:49]
	v_mfma_f32_16x16x32_bf16 v[42:45], v[162:165], v[198:201], v[42:45]
	v_mfma_f32_16x16x32_bf16 v[30:33], v[130:133], v[220:223], v[30:33]
	v_mfma_f32_16x16x32_bf16 v[26:29], v[162:165], v[220:223], v[26:29]
	v_mfma_f32_16x16x32_bf16 v[14:17], v[130:133], v[228:231], v[14:17]
	v_mfma_f32_16x16x32_bf16 v[10:13], v[162:165], v[228:231], v[10:13]
	v_mfma_f32_16x16x32_bf16 v[62:65], v[158:161], v[194:197], v[62:65]
	v_mfma_f32_16x16x32_bf16 v[58:61], v[170:173], v[194:197], v[58:61]
	v_mfma_f32_16x16x32_bf16 v[46:49], v[158:161], v[216:219], v[46:49]
	v_mfma_f32_16x16x32_bf16 v[42:45], v[170:173], v[216:219], v[42:45]
	v_mfma_f32_16x16x32_bf16 v[30:33], v[158:161], v[224:227], v[30:33]
	v_mfma_f32_16x16x32_bf16 v[26:29], v[170:173], v[224:227], v[26:29]
	v_mfma_f32_16x16x32_bf16 v[14:17], v[158:161], v[232:235], v[14:17]
	v_mfma_f32_16x16x32_bf16 v[10:13], v[170:173], v[232:235], v[10:13]
	s_setprio 0
	s_setprio 1
	v_mfma_f32_16x16x32_bf16 v[54:57], v[174:177], v[190:193], v[54:57]
	v_mfma_f32_16x16x32_bf16 v[50:53], v[182:185], v[190:193], v[50:53]
	v_mfma_f32_16x16x32_bf16 v[38:41], v[174:177], v[198:201], v[38:41]
	v_mfma_f32_16x16x32_bf16 v[34:37], v[182:185], v[198:201], v[34:37]
	v_mfma_f32_16x16x32_bf16 v[22:25], v[174:177], v[220:223], v[22:25]
	v_mfma_f32_16x16x32_bf16 v[18:21], v[182:185], v[220:223], v[18:21]
	v_mfma_f32_16x16x32_bf16 v[6:9], v[174:177], v[228:231], v[6:9]
	v_mfma_f32_16x16x32_bf16 v[2:5], v[182:185], v[228:231], v[2:5]
	v_mfma_f32_16x16x32_bf16 v[54:57], v[178:181], v[194:197], v[54:57]
	v_mfma_f32_16x16x32_bf16 v[50:53], v[186:189], v[194:197], v[50:53]
	v_mfma_f32_16x16x32_bf16 v[38:41], v[178:181], v[216:219], v[38:41]
	v_mfma_f32_16x16x32_bf16 v[34:37], v[186:189], v[216:219], v[34:37]
	v_mfma_f32_16x16x32_bf16 v[22:25], v[178:181], v[224:227], v[22:25]
	v_mfma_f32_16x16x32_bf16 v[18:21], v[186:189], v[224:227], v[18:21]
	v_mfma_f32_16x16x32_bf16 v[6:9], v[178:181], v[232:235], v[6:9]
	v_mfma_f32_16x16x32_bf16 v[2:5], v[186:189], v[232:235], v[2:5]
	s_setprio 0
	s_barrier
	s_add_i32 s59, s59, 2
	s_add_u32 s57, s57, 0x100
	s_addc_u32 s58, s58, 0
	s_add_u32 s8, s8, 0x100
	s_addc_u32 s9, s9, 0
	s_cmp_gt_u32 s59, 29
	s_cbranch_scc0 .LBB0_140
	s_and_b64 vcc, exec, s[20:21]
	s_cbranch_vccz .LBB0_143
	s_barrier

.LBB0_772:
	s_add_u32 s60, s26, 0xfff80080
	s_addc_u32 s61, s27, -1
	s_add_i32 s62, 0, 0x10000
	s_cmp_eq_u32 s59, 28
	s_cselect_b32 s87, s0, s61
	s_cselect_b32 s86, s1, s60
	v_add_u32_e32 v140, s62, v143
	s_cselect_b32 s81, s13, s58
	s_cselect_b32 s80, s15, s57
	s_add_i32 s63, 0, 0x14000
	ds_read_b128 v[156:159], v140
	ds_read_b128 v[160:163], v140 offset:1024
	ds_read_b128 v[164:167], v140 offset:2048
	ds_read_b128 v[168:171], v140 offset:3072
	v_add_u32_e32 v140, s63, v143
	ds_read_b128 v[172:175], v140
	ds_read_b128 v[176:179], v140 offset:1024
	ds_read_b128 v[180:183], v140 offset:2048
	ds_read_b128 v[184:187], v140 offset:3072
	s_mov_b32 m0, s53
	s_nop 0
	global_load_lds_dwordx4 v132, s[100:101]
	s_add_i32 m0, s48, 0xc000
	ds_read_b128 v[188:191], v145
	ds_read_b128 v[192:195], v145 offset:1024
	ds_read_b128 v[196:199], v145 offset:2048
	ds_read_b128 v[200:203], v145 offset:3072
	ds_read_b128 v[218:221], v145 offset:4096
	ds_read_b128 v[222:225], v145 offset:5120
	ds_read_b128 v[226:229], v145 offset:6144
	ds_read_b128 v[230:233], v145 offset:7168
	global_load_lds_dwordx4 v138, s[26:27]
	s_add_i32 m0, s48, 0xe000
	s_nop 0
	global_load_lds_dwordx4 v136, s[26:27]
	s_waitcnt vmcnt(8)
	s_waitcnt lgkmcnt(0)
	s_barrier
	s_setprio 1
	s_waitcnt lgkmcnt(0)
	v_mfma_f32_16x16x32_bf16 v[126:129], v[156:159], v[188:191], v[126:129]
	v_mfma_f32_16x16x32_bf16 v[122:125], v[164:167], v[188:191], v[122:125]
	v_mfma_f32_16x16x32_bf16 v[118:121], v[156:159], v[196:199], v[118:121]
	v_mfma_f32_16x16x32_bf16 v[110:113], v[164:167], v[196:199], v[110:113]
	v_mfma_f32_16x16x32_bf16 v[102:105], v[156:159], v[218:221], v[102:105]
	v_mfma_f32_16x16x32_bf16 v[94:97], v[164:167], v[218:221], v[94:97]
	v_mfma_f32_16x16x32_bf16 v[86:89], v[156:159], v[226:229], v[86:89]
	v_mfma_f32_16x16x32_bf16 v[78:81], v[164:167], v[226:229], v[78:81]
	v_mfma_f32_16x16x32_bf16 v[126:129], v[160:163], v[192:195], v[126:129]
	v_mfma_f32_16x16x32_bf16 v[122:125], v[168:171], v[192:195], v[122:125]
	v_mfma_f32_16x16x32_bf16 v[118:121], v[160:163], v[200:203], v[118:121]
	v_mfma_f32_16x16x32_bf16 v[110:113], v[168:171], v[200:203], v[110:113]
	v_mfma_f32_16x16x32_bf16 v[102:105], v[160:163], v[222:225], v[102:105]
	v_mfma_f32_16x16x32_bf16 v[94:97], v[168:171], v[222:225], v[94:97]
	v_mfma_f32_16x16x32_bf16 v[86:89], v[160:163], v[230:233], v[86:89]
	v_mfma_f32_16x16x32_bf16 v[78:81], v[168:171], v[230:233], v[78:81]
	s_setprio 0
	s_setprio 1
	v_mfma_f32_16x16x32_bf16 v[114:117], v[172:175], v[188:191], v[114:117]
	v_mfma_f32_16x16x32_bf16 v[106:109], v[180:183], v[188:191], v[106:109]
	v_mfma_f32_16x16x32_bf16 v[98:101], v[172:175], v[196:199], v[98:101]
	v_mfma_f32_16x16x32_bf16 v[90:93], v[180:183], v[196:199], v[90:93]
	v_mfma_f32_16x16x32_bf16 v[82:85], v[172:175], v[218:221], v[82:85]
	v_mfma_f32_16x16x32_bf16 v[74:77], v[180:183], v[218:221], v[74:77]
	v_mfma_f32_16x16x32_bf16 v[70:73], v[172:175], v[226:229], v[70:73]
	v_mfma_f32_16x16x32_bf16 v[66:69], v[180:183], v[226:229], v[66:69]
	v_mfma_f32_16x16x32_bf16 v[114:117], v[176:179], v[192:195], v[114:117]
	v_mfma_f32_16x16x32_bf16 v[106:109], v[184:187], v[192:195], v[106:109]
	v_mfma_f32_16x16x32_bf16 v[98:101], v[176:179], v[200:203], v[98:101]
	v_mfma_f32_16x16x32_bf16 v[90:93], v[184:187], v[200:203], v[90:93]
	v_mfma_f32_16x16x32_bf16 v[82:85], v[176:179], v[222:225], v[82:85]
	v_mfma_f32_16x16x32_bf16 v[74:77], v[184:187], v[222:225], v[74:77]
	v_mfma_f32_16x16x32_bf16 v[70:73], v[176:179], v[230:233], v[70:73]
	v_mfma_f32_16x16x32_bf16 v[66:69], v[184:187], v[230:233], v[66:69]
	s_setprio 0
	s_barrier
	s_add_i32 s60, s62, s29
	s_add_u32 s88, s80, s44
	s_addc_u32 s89, s81, s45
	s_mov_b32 m0, s60
	ds_read_b128 v[188:191], v145 offset:16384
	ds_read_b128 v[192:195], v145 offset:17408
	ds_read_b128 v[196:199], v145 offset:18432
	ds_read_b128 v[200:203], v145 offset:19456
	ds_read_b128 v[218:221], v145 offset:20480
	ds_read_b128 v[222:225], v145 offset:21504
	ds_read_b128 v[226:229], v145 offset:22528
	ds_read_b128 v[230:233], v145 offset:23552
	global_load_lds_dwordx4 v0, s[80:81]
	s_add_i32 m0, s60, 0x2000
	s_add_u32 s60, s80, 0x80000
	s_addc_u32 s61, s81, 0
	s_add_i32 s62, s63, s29
	global_load_lds_dwordx4 v130, s[80:81]
	s_mov_b32 m0, s62
	s_add_u32 s100, s86, s44
	s_addc_u32 s101, s87, s45
	global_load_lds_dwordx4 v0, s[60:61]
	s_add_i32 m0, s62, 0x2000
	s_nop 0
	global_load_lds_dwordx4 v130, s[60:61]
	s_mov_b32 m0, s48
	s_nop 0
	global_load_lds_dwordx4 v134, s[86:87]
	s_waitcnt vmcnt(7)
	s_waitcnt lgkmcnt(0)
	s_barrier
	s_setprio 1
	s_waitcnt lgkmcnt(0)
	v_mfma_f32_16x16x32_bf16 v[62:65], v[156:159], v[188:191], v[62:65]
	v_mfma_f32_16x16x32_bf16 v[58:61], v[164:167], v[188:191], v[58:61]
	v_mfma_f32_16x16x32_bf16 v[54:57], v[156:159], v[196:199], v[54:57]
	v_mfma_f32_16x16x32_bf16 v[46:49], v[164:167], v[196:199], v[46:49]
	v_mfma_f32_16x16x32_bf16 v[38:41], v[156:159], v[218:221], v[38:41]
	v_mfma_f32_16x16x32_bf16 v[30:33], v[164:167], v[218:221], v[30:33]
	v_mfma_f32_16x16x32_bf16 v[22:25], v[156:159], v[226:229], v[22:25]
	v_mfma_f32_16x16x32_bf16 v[14:17], v[164:167], v[226:229], v[14:17]
	v_mfma_f32_16x16x32_bf16 v[62:65], v[160:163], v[192:195], v[62:65]
	v_mfma_f32_16x16x32_bf16 v[58:61], v[168:171], v[192:195], v[58:61]
	v_mfma_f32_16x16x32_bf16 v[54:57], v[160:163], v[200:203], v[54:57]
	v_mfma_f32_16x16x32_bf16 v[46:49], v[168:171], v[200:203], v[46:49]
	v_mfma_f32_16x16x32_bf16 v[38:41], v[160:163], v[222:225], v[38:41]
	v_mfma_f32_16x16x32_bf16 v[30:33], v[168:171], v[222:225], v[30:33]
	v_mfma_f32_16x16x32_bf16 v[22:25], v[160:163], v[230:233], v[22:25]
	v_mfma_f32_16x16x32_bf16 v[14:17], v[168:171], v[230:233], v[14:17]
	s_setprio 0
	s_setprio 1
	v_mfma_f32_16x16x32_bf16 v[50:53], v[172:175], v[188:191], v[50:53]
	v_mfma_f32_16x16x32_bf16 v[42:45], v[180:183], v[188:191], v[42:45]
	v_mfma_f32_16x16x32_bf16 v[34:37], v[172:175], v[196:199], v[34:37]
	v_mfma_f32_16x16x32_bf16 v[26:29], v[180:183], v[196:199], v[26:29]
	v_mfma_f32_16x16x32_bf16 v[18:21], v[172:175], v[218:221], v[18:21]
	v_mfma_f32_16x16x32_bf16 v[10:13], v[180:183], v[218:221], v[10:13]
	v_mfma_f32_16x16x32_bf16 v[6:9], v[172:175], v[226:229], v[6:9]
	v_mfma_f32_16x16x32_bf16 v[2:5], v[180:183], v[226:229], v[2:5]
	v_mfma_f32_16x16x32_bf16 v[50:53], v[176:179], v[192:195], v[50:53]
	v_mfma_f32_16x16x32_bf16 v[42:45], v[184:187], v[192:195], v[42:45]
	v_mfma_f32_16x16x32_bf16 v[34:37], v[176:179], v[200:203], v[34:37]
	v_mfma_f32_16x16x32_bf16 v[26:29], v[184:187], v[200:203], v[26:29]
	v_mfma_f32_16x16x32_bf16 v[18:21], v[176:179], v[222:225], v[18:21]
	v_mfma_f32_16x16x32_bf16 v[10:13], v[184:187], v[222:225], v[10:13]
	v_mfma_f32_16x16x32_bf16 v[6:9], v[176:179], v[230:233], v[6:9]
	v_mfma_f32_16x16x32_bf16 v[2:5], v[184:187], v[230:233], v[2:5]
	s_setprio 0
	s_barrier
	s_add_i32 s62, 0, 0x18000
	s_add_i32 s63, 0, 0x1c000
	v_add_u32_e32 v168, s62, v143
	v_add_u32_e32 v184, s63, v143
	ds_read_b128 v[156:159], v168
	ds_read_b128 v[160:163], v168 offset:1024
	ds_read_b128 v[164:167], v168 offset:2048
	ds_read_b128 v[168:171], v168 offset:3072
	ds_read_b128 v[172:175], v184
	ds_read_b128 v[176:179], v184 offset:1024
	ds_read_b128 v[180:183], v184 offset:2048
	ds_read_b128 v[184:187], v184 offset:3072
	s_mov_b32 m0, s49
	s_nop 0
	global_load_lds_dwordx4 v132, s[86:87]
	s_add_u32 s60, s86, 0x80000
	s_addc_u32 s61, s87, 0
	s_mov_b32 m0, s50
	ds_read_b128 v[188:191], v145 offset:32768
	ds_read_b128 v[192:195], v145 offset:33792
	ds_read_b128 v[196:199], v145 offset:34816
	ds_read_b128 v[200:203], v145 offset:35840
	ds_read_b128 v[218:221], v145 offset:36864
	ds_read_b128 v[222:225], v145 offset:37888
	ds_read_b128 v[226:229], v145 offset:38912
	ds_read_b128 v[230:233], v145 offset:39936
	global_load_lds_dwordx4 v134, s[60:61]
	s_mov_b32 m0, s51
	s_nop 0
	global_load_lds_dwordx4 v132, s[60:61]
	s_waitcnt vmcnt(8)
	s_waitcnt lgkmcnt(0)
	s_barrier
	s_setprio 1
	s_waitcnt lgkmcnt(0)
	v_mfma_f32_16x16x32_bf16 v[126:129], v[156:159], v[188:191], v[126:129]
	v_mfma_f32_16x16x32_bf16 v[122:125], v[164:167], v[188:191], v[122:125]
	v_mfma_f32_16x16x32_bf16 v[118:121], v[156:159], v[196:199], v[118:121]
	v_mfma_f32_16x16x32_bf16 v[110:113], v[164:167], v[196:199], v[110:113]
	v_mfma_f32_16x16x32_bf16 v[102:105], v[156:159], v[218:221], v[102:105]
	v_mfma_f32_16x16x32_bf16 v[94:97], v[164:167], v[218:221], v[94:97]
	v_mfma_f32_16x16x32_bf16 v[86:89], v[156:159], v[226:229], v[86:89]
	v_mfma_f32_16x16x32_bf16 v[78:81], v[164:167], v[226:229], v[78:81]
	v_mfma_f32_16x16x32_bf16 v[126:129], v[160:163], v[192:195], v[126:129]
	v_mfma_f32_16x16x32_bf16 v[122:125], v[168:171], v[192:195], v[122:125]
	v_mfma_f32_16x16x32_bf16 v[118:121], v[160:163], v[200:203], v[118:121]
	v_mfma_f32_16x16x32_bf16 v[110:113], v[168:171], v[200:203], v[110:113]
	v_mfma_f32_16x16x32_bf16 v[102:105], v[160:163], v[222:225], v[102:105]
	v_mfma_f32_16x16x32_bf16 v[94:97], v[168:171], v[222:225], v[94:97]
	v_mfma_f32_16x16x32_bf16 v[86:89], v[160:163], v[230:233], v[86:89]
	v_mfma_f32_16x16x32_bf16 v[78:81], v[168:171], v[230:233], v[78:81]
	s_setprio 0
	s_setprio 1
	v_mfma_f32_16x16x32_bf16 v[114:117], v[172:175], v[188:191], v[114:117]
	v_mfma_f32_16x16x32_bf16 v[106:109], v[180:183], v[188:191], v[106:109]
	v_mfma_f32_16x16x32_bf16 v[98:101], v[172:175], v[196:199], v[98:101]
	v_mfma_f32_16x16x32_bf16 v[90:93], v[180:183], v[196:199], v[90:93]
	v_mfma_f32_16x16x32_bf16 v[82:85], v[172:175], v[218:221], v[82:85]
	v_mfma_f32_16x16x32_bf16 v[74:77], v[180:183], v[218:221], v[74:77]
	v_mfma_f32_16x16x32_bf16 v[70:73], v[172:175], v[226:229], v[70:73]
	v_mfma_f32_16x16x32_bf16 v[66:69], v[180:183], v[226:229], v[66:69]
	v_mfma_f32_16x16x32_bf16 v[114:117], v[176:179], v[192:195], v[114:117]
	v_mfma_f32_16x16x32_bf16 v[106:109], v[184:187], v[192:195], v[106:109]
	v_mfma_f32_16x16x32_bf16 v[98:101], v[176:179], v[200:203], v[98:101]
	v_mfma_f32_16x16x32_bf16 v[90:93], v[184:187], v[200:203], v[90:93]
	v_mfma_f32_16x16x32_bf16 v[82:85], v[176:179], v[222:225], v[82:85]
	v_mfma_f32_16x16x32_bf16 v[74:77], v[184:187], v[222:225], v[74:77]
	v_mfma_f32_16x16x32_bf16 v[70:73], v[176:179], v[230:233], v[70:73]
	v_mfma_f32_16x16x32_bf16 v[66:69], v[184:187], v[230:233], v[66:69]
	s_setprio 0
	s_barrier
	s_add_i32 s60, s62, s29
	s_mov_b32 m0, s60
	ds_read_b128 v[188:191], v145 offset:49152
	ds_read_b128 v[192:195], v145 offset:50176
	ds_read_b128 v[196:199], v145 offset:51200
	ds_read_b128 v[200:203], v145 offset:52224
	ds_read_b128 v[218:221], v145 offset:53248
	ds_read_b128 v[222:225], v145 offset:54272
	ds_read_b128 v[226:229], v145 offset:55296
	ds_read_b128 v[230:233], v145 offset:56320
	global_load_lds_dwordx4 v0, s[88:89]
	s_add_i32 m0, s60, 0x2000
	s_add_u32 s60, s80, 0x80080
	s_addc_u32 s61, s81, 0
	s_add_i32 s62, s63, s29
	global_load_lds_dwordx4 v130, s[88:89]
	s_mov_b32 m0, s62
	s_nop 0
	global_load_lds_dwordx4 v0, s[60:61]
	s_add_i32 m0, s62, 0x2000
	s_nop 0
	global_load_lds_dwordx4 v130, s[60:61]
	s_mov_b32 m0, s52
	s_nop 0
	global_load_lds_dwordx4 v134, s[100:101]
	s_waitcnt vmcnt(7)
	s_waitcnt lgkmcnt(0)
	s_barrier
	s_setprio 1
	s_waitcnt lgkmcnt(0)
	v_mfma_f32_16x16x32_bf16 v[62:65], v[156:159], v[188:191], v[62:65]
	v_mfma_f32_16x16x32_bf16 v[58:61], v[164:167], v[188:191], v[58:61]
	v_mfma_f32_16x16x32_bf16 v[54:57], v[156:159], v[196:199], v[54:57]
	v_mfma_f32_16x16x32_bf16 v[46:49], v[164:167], v[196:199], v[46:49]
	v_mfma_f32_16x16x32_bf16 v[38:41], v[156:159], v[218:221], v[38:41]
	v_mfma_f32_16x16x32_bf16 v[30:33], v[164:167], v[218:221], v[30:33]
	v_mfma_f32_16x16x32_bf16 v[22:25], v[156:159], v[226:229], v[22:25]
	v_mfma_f32_16x16x32_bf16 v[14:17], v[164:167], v[226:229], v[14:17]
	v_mfma_f32_16x16x32_bf16 v[62:65], v[160:163], v[192:195], v[62:65]
	v_mfma_f32_16x16x32_bf16 v[58:61], v[168:171], v[192:195], v[58:61]
	v_mfma_f32_16x16x32_bf16 v[54:57], v[160:163], v[200:203], v[54:57]
	v_mfma_f32_16x16x32_bf16 v[46:49], v[168:171], v[200:203], v[46:49]
	v_mfma_f32_16x16x32_bf16 v[38:41], v[160:163], v[222:225], v[38:41]
	v_mfma_f32_16x16x32_bf16 v[30:33], v[168:171], v[222:225], v[30:33]
	v_mfma_f32_16x16x32_bf16 v[22:25], v[160:163], v[230:233], v[22:25]
	v_mfma_f32_16x16x32_bf16 v[14:17], v[168:171], v[230:233], v[14:17]
	s_setprio 0
	s_setprio 1
	v_mfma_f32_16x16x32_bf16 v[50:53], v[172:175], v[188:191], v[50:53]
	v_mfma_f32_16x16x32_bf16 v[42:45], v[180:183], v[188:191], v[42:45]
	v_mfma_f32_16x16x32_bf16 v[34:37], v[172:175], v[196:199], v[34:37]
	v_mfma_f32_16x16x32_bf16 v[26:29], v[180:183], v[196:199], v[26:29]
	v_mfma_f32_16x16x32_bf16 v[18:21], v[172:175], v[218:221], v[18:21]
	v_mfma_f32_16x16x32_bf16 v[10:13], v[180:183], v[218:221], v[10:13]
	v_mfma_f32_16x16x32_bf16 v[6:9], v[172:175], v[226:229], v[6:9]
	v_mfma_f32_16x16x32_bf16 v[2:5], v[180:183], v[226:229], v[2:5]
	v_mfma_f32_16x16x32_bf16 v[50:53], v[176:179], v[192:195], v[50:53]
	v_mfma_f32_16x16x32_bf16 v[42:45], v[184:187], v[192:195], v[42:45]
	v_mfma_f32_16x16x32_bf16 v[34:37], v[176:179], v[200:203], v[34:37]
	v_mfma_f32_16x16x32_bf16 v[26:29], v[184:187], v[200:203], v[26:29]
	v_mfma_f32_16x16x32_bf16 v[18:21], v[176:179], v[222:225], v[18:21]
	v_mfma_f32_16x16x32_bf16 v[10:13], v[184:187], v[222:225], v[10:13]
	v_mfma_f32_16x16x32_bf16 v[6:9], v[176:179], v[230:233], v[6:9]
	v_mfma_f32_16x16x32_bf16 v[2:5], v[184:187], v[230:233], v[2:5]
	s_setprio 0
	s_barrier
	s_add_i32 s59, s59, 2
	s_add_u32 s57, s57, 0x100
	s_addc_u32 s58, s58, 0
	s_add_u32 s26, s26, 0x100
	s_addc_u32 s27, s27, 0
	s_cmp_gt_u32 s59, 29
	s_cbranch_scc0 .LBB0_772
	s_and_b64 vcc, exec, s[10:11]
	v_readlane_b32 s58, v254, 35
	v_readlane_b32 s59, v254, 36
	s_cbranch_vccz .LBB0_775
	s_barrier
